# adaLN GEMV double-buffered with a second register set: the loads of trip t+1 are issued before trip t is consumed (8-16 ada_w loads in flight)
# speedup vs baseline: 1.0054x; 1.0054x over previous
; __device__ __forceinline__ void phase_prep(const Params& P, LAS unsigned char* lds, int l, const XcdBarrier& bar) {
;     ...
; #pragma unroll 8
;         for (int kk = 0; kk < 64; ++kk) { const f32x4 wv = __builtin_nontemporal_load((const f32x4*)(wp + (size_t)kk * 32 * NMOD)); const int k = kg + 32 * kk;
;             a0 += wv * sc[k]; a1 += wv * sc[DM + k]; a2 += wv * sc[2 * DM + k]; a3 += wv * sc[3 * DM + k]; }
.Lada_loop:
	v_lshl_add_u64 v[218:219], v[38:39], 0, s[58:59]
	global_load_dwordx4 v[186:189], v[218:219], off nt
	v_add_co_u32_e32 v190, vcc, s2, v218
	s_nop 1
	v_addc_co_u32_e32 v191, vcc, 0, v219, vcc
	global_load_dwordx4 v[190:193], v[190:191], off nt
	v_add_co_u32_e32 v194, vcc, s9, v218
	s_nop 1
	v_addc_co_u32_e32 v195, vcc, 0, v219, vcc
	global_load_dwordx4 v[194:197], v[194:195], off nt
	v_add_co_u32_e32 v198, vcc, s19, v218
	s_nop 1
	v_addc_co_u32_e32 v199, vcc, 0, v219, vcc
	global_load_dwordx4 v[198:201], v[198:199], off nt
	v_add_co_u32_e32 v202, vcc, s24, v218
	s_nop 1
	v_addc_co_u32_e32 v203, vcc, 0, v219, vcc
	global_load_dwordx4 v[202:205], v[202:203], off nt
	v_add_co_u32_e32 v206, vcc, s25, v218
	s_nop 1
	v_addc_co_u32_e32 v207, vcc, 0, v219, vcc
	global_load_dwordx4 v[206:209], v[206:207], off nt
	v_add_co_u32_e32 v210, vcc, s29, v218
	s_nop 1
	v_addc_co_u32_e32 v211, vcc, 0, v219, vcc
	global_load_dwordx4 v[210:213], v[210:211], off nt
	v_add_co_u32_e32 v214, vcc, s30, v218
	s_nop 1
	v_addc_co_u32_e32 v215, vcc, 0, v219, vcc
	global_load_dwordx4 v[214:217], v[214:215], off nt
	s_add_u32 s58, s58, 0x1200000
	s_addc_u32 s59, s59, 0
	v_add_u32_e32 v37, 0x2000, v2
	v_add_u32_e32 v220, 0x4000, v2
	v_add_u32_e32 v221, 0x6000, v2
	ds_read2_b32 v[40:41], v2 offset1:32
	ds_read2_b32 v[44:45], v2 offset0:64 offset1:96
	ds_read2_b32 v[46:47], v2 offset0:128 offset1:160
	ds_read2_b32 v[106:107], v2 offset0:192 offset1:224
	ds_read2_b32 v[108:109], v37 offset1:32
	ds_read2_b32 v[110:111], v220 offset1:32
	ds_read2_b32 v[112:113], v221 offset1:32
	ds_read2_b32 v[114:115], v37 offset0:64 offset1:96
	ds_read2_b32 v[116:117], v220 offset0:64 offset1:96
	ds_read2_b32 v[118:119], v221 offset0:64 offset1:96
	ds_read2_b32 v[120:121], v37 offset0:128 offset1:160
	ds_read2_b32 v[122:123], v220 offset0:128 offset1:160
	ds_read2_b32 v[124:125], v221 offset0:128 offset1:160
	ds_read2_b32 v[126:127], v37 offset0:192 offset1:224
	ds_read2_b32 v[128:129], v220 offset0:192 offset1:224
	ds_read2_b32 v[130:131], v221 offset0:192 offset1:224
	s_waitcnt lgkmcnt(0)
	v_mov_b32_e32 v138, v109
	v_mov_b32_e32 v42, v41
	v_mov_b32_e32 v140, v111
	v_mov_b32_e32 v142, v113
	v_mov_b32_e32 v132, v45
	v_mov_b32_e32 v144, v115
	v_mov_b32_e32 v146, v117
	v_mov_b32_e32 v148, v119
	v_mov_b32_e32 v134, v47
	v_mov_b32_e32 v150, v121
	v_mov_b32_e32 v152, v123
	v_mov_b32_e32 v154, v125
	v_mov_b32_e32 v136, v107
	v_mov_b32_e32 v156, v127
	v_mov_b32_e32 v158, v129
	v_mov_b32_e32 v160, v131
	v_add_u32_e32 v2, 0x400, v2
	s_waitcnt vmcnt(15)
	v_pk_fma_f32 v[16:17], v[74:75], v[40:41], v[16:17] op_sel_hi:[1,0,1]
	v_pk_fma_f32 v[18:19], v[76:77], v[40:41], v[18:19] op_sel_hi:[1,0,1]
	v_pk_fma_f32 v[12:13], v[74:75], v[108:109], v[12:13] op_sel_hi:[1,0,1]
	v_pk_fma_f32 v[14:15], v[76:77], v[108:109], v[14:15] op_sel_hi:[1,0,1]
	v_pk_fma_f32 v[8:9], v[74:75], v[110:111], v[8:9] op_sel_hi:[1,0,1]
	v_pk_fma_f32 v[10:11], v[76:77], v[110:111], v[10:11] op_sel_hi:[1,0,1]
	v_pk_fma_f32 v[4:5], v[74:75], v[112:113], v[4:5] op_sel_hi:[1,0,1]
	v_pk_fma_f32 v[6:7], v[76:77], v[112:113], v[6:7] op_sel_hi:[1,0,1]
	s_waitcnt vmcnt(14)
	v_pk_fma_f32 v[16:17], v[78:79], v[42:43], v[16:17] op_sel_hi:[1,0,1]
	v_pk_fma_f32 v[18:19], v[80:81], v[42:43], v[18:19] op_sel_hi:[1,0,1]
	v_pk_fma_f32 v[12:13], v[78:79], v[138:139], v[12:13] op_sel_hi:[1,0,1]
	v_pk_fma_f32 v[14:15], v[80:81], v[138:139], v[14:15] op_sel_hi:[1,0,1]
	v_pk_fma_f32 v[8:9], v[78:79], v[140:141], v[8:9] op_sel_hi:[1,0,1]
	v_pk_fma_f32 v[10:11], v[80:81], v[140:141], v[10:11] op_sel_hi:[1,0,1]
	v_pk_fma_f32 v[4:5], v[78:79], v[142:143], v[4:5] op_sel_hi:[1,0,1]
	v_pk_fma_f32 v[6:7], v[80:81], v[142:143], v[6:7] op_sel_hi:[1,0,1]
	s_waitcnt vmcnt(13)
	v_pk_fma_f32 v[18:19], v[84:85], v[44:45], v[18:19] op_sel_hi:[1,0,1]
	v_pk_fma_f32 v[16:17], v[82:83], v[44:45], v[16:17] op_sel_hi:[1,0,1]
	v_pk_fma_f32 v[14:15], v[84:85], v[114:115], v[14:15] op_sel_hi:[1,0,1]
	v_pk_fma_f32 v[12:13], v[82:83], v[114:115], v[12:13] op_sel_hi:[1,0,1]
	v_pk_fma_f32 v[10:11], v[84:85], v[116:117], v[10:11] op_sel_hi:[1,0,1]
	v_pk_fma_f32 v[8:9], v[82:83], v[116:117], v[8:9] op_sel_hi:[1,0,1]
	v_pk_fma_f32 v[6:7], v[84:85], v[118:119], v[6:7] op_sel_hi:[1,0,1]
	v_pk_fma_f32 v[4:5], v[82:83], v[118:119], v[4:5] op_sel_hi:[1,0,1]
	s_waitcnt vmcnt(12)
	v_pk_fma_f32 v[18:19], v[88:89], v[132:133], v[18:19] op_sel_hi:[1,0,1]
	v_pk_fma_f32 v[16:17], v[86:87], v[132:133], v[16:17] op_sel_hi:[1,0,1]
	v_pk_fma_f32 v[14:15], v[88:89], v[144:145], v[14:15] op_sel_hi:[1,0,1]
	v_pk_fma_f32 v[12:13], v[86:87], v[144:145], v[12:13] op_sel_hi:[1,0,1]
	v_pk_fma_f32 v[10:11], v[88:89], v[146:147], v[10:11] op_sel_hi:[1,0,1]
	v_pk_fma_f32 v[8:9], v[86:87], v[146:147], v[8:9] op_sel_hi:[1,0,1]
	v_pk_fma_f32 v[6:7], v[88:89], v[148:149], v[6:7] op_sel_hi:[1,0,1]
	v_pk_fma_f32 v[4:5], v[86:87], v[148:149], v[4:5] op_sel_hi:[1,0,1]
	s_waitcnt vmcnt(11)
	v_pk_fma_f32 v[18:19], v[92:93], v[46:47], v[18:19] op_sel_hi:[1,0,1]
	v_pk_fma_f32 v[16:17], v[90:91], v[46:47], v[16:17] op_sel_hi:[1,0,1]
	v_pk_fma_f32 v[14:15], v[92:93], v[120:121], v[14:15] op_sel_hi:[1,0,1]
	v_pk_fma_f32 v[12:13], v[90:91], v[120:121], v[12:13] op_sel_hi:[1,0,1]
	v_pk_fma_f32 v[10:11], v[92:93], v[122:123], v[10:11] op_sel_hi:[1,0,1]
	v_pk_fma_f32 v[8:9], v[90:91], v[122:123], v[8:9] op_sel_hi:[1,0,1]
	v_pk_fma_f32 v[6:7], v[92:93], v[124:125], v[6:7] op_sel_hi:[1,0,1]
	v_pk_fma_f32 v[4:5], v[90:91], v[124:125], v[4:5] op_sel_hi:[1,0,1]
	s_waitcnt vmcnt(10)
; __device__ __forceinline__ void phase_prep(const Params& P, LAS unsigned char* lds, int l, const XcdBarrier& bar) {
;     ...
; #pragma unroll 8
;         for (int kk = 0; kk < 64; ++kk) { const f32x4 wv = __builtin_nontemporal_load((const f32x4*)(wp + (size_t)kk * 32 * NMOD)); const int k = kg + 32 * kk;
;             a0 += wv * sc[k]; a1 += wv * sc[DM + k]; a2 += wv * sc[2 * DM + k]; a3 += wv * sc[3 * DM + k]; }
	v_pk_fma_f32 v[18:19], v[96:97], v[134:135], v[18:19] op_sel_hi:[1,0,1]
	v_pk_fma_f32 v[16:17], v[94:95], v[134:135], v[16:17] op_sel_hi:[1,0,1]
	v_pk_fma_f32 v[14:15], v[96:97], v[150:151], v[14:15] op_sel_hi:[1,0,1]
	v_pk_fma_f32 v[12:13], v[94:95], v[150:151], v[12:13] op_sel_hi:[1,0,1]
	v_pk_fma_f32 v[10:11], v[96:97], v[152:153], v[10:11] op_sel_hi:[1,0,1]
	v_pk_fma_f32 v[8:9], v[94:95], v[152:153], v[8:9] op_sel_hi:[1,0,1]
	v_pk_fma_f32 v[6:7], v[96:97], v[154:155], v[6:7] op_sel_hi:[1,0,1]
	v_pk_fma_f32 v[4:5], v[94:95], v[154:155], v[4:5] op_sel_hi:[1,0,1]
	s_waitcnt vmcnt(9)
	v_pk_fma_f32 v[18:19], v[100:101], v[106:107], v[18:19] op_sel_hi:[1,0,1]
	v_pk_fma_f32 v[16:17], v[98:99], v[106:107], v[16:17] op_sel_hi:[1,0,1]
	v_pk_fma_f32 v[14:15], v[100:101], v[126:127], v[14:15] op_sel_hi:[1,0,1]
	v_pk_fma_f32 v[12:13], v[98:99], v[126:127], v[12:13] op_sel_hi:[1,0,1]
	v_pk_fma_f32 v[10:11], v[100:101], v[128:129], v[10:11] op_sel_hi:[1,0,1]
	v_pk_fma_f32 v[8:9], v[98:99], v[128:129], v[8:9] op_sel_hi:[1,0,1]
	v_pk_fma_f32 v[6:7], v[100:101], v[130:131], v[6:7] op_sel_hi:[1,0,1]
	v_pk_fma_f32 v[4:5], v[98:99], v[130:131], v[4:5] op_sel_hi:[1,0,1]
	s_waitcnt vmcnt(8)
	v_pk_fma_f32 v[18:19], v[104:105], v[136:137], v[18:19] op_sel_hi:[1,0,1]
	v_pk_fma_f32 v[16:17], v[102:103], v[136:137], v[16:17] op_sel_hi:[1,0,1]
	v_pk_fma_f32 v[14:15], v[104:105], v[156:157], v[14:15] op_sel_hi:[1,0,1]
	v_pk_fma_f32 v[12:13], v[102:103], v[156:157], v[12:13] op_sel_hi:[1,0,1]
	v_pk_fma_f32 v[10:11], v[104:105], v[158:159], v[10:11] op_sel_hi:[1,0,1]
	v_pk_fma_f32 v[8:9], v[102:103], v[158:159], v[8:9] op_sel_hi:[1,0,1]
	v_pk_fma_f32 v[6:7], v[104:105], v[160:161], v[6:7] op_sel_hi:[1,0,1]
	v_pk_fma_f32 v[4:5], v[102:103], v[160:161], v[4:5] op_sel_hi:[1,0,1]
	v_lshl_add_u64 v[218:219], v[38:39], 0, s[58:59]
	global_load_dwordx4 v[74:77], v[218:219], off nt
	v_add_co_u32_e32 v78, vcc, s2, v218
	s_nop 1
	v_addc_co_u32_e32 v79, vcc, 0, v219, vcc
	global_load_dwordx4 v[78:81], v[78:79], off nt
	v_add_co_u32_e32 v82, vcc, s9, v218
	s_nop 1
	v_addc_co_u32_e32 v83, vcc, 0, v219, vcc
	global_load_dwordx4 v[82:85], v[82:83], off nt
	v_add_co_u32_e32 v86, vcc, s19, v218
	s_nop 1
	v_addc_co_u32_e32 v87, vcc, 0, v219, vcc
	global_load_dwordx4 v[86:89], v[86:87], off nt
	v_add_co_u32_e32 v90, vcc, s24, v218
	s_nop 1
	v_addc_co_u32_e32 v91, vcc, 0, v219, vcc
	global_load_dwordx4 v[90:93], v[90:91], off nt
	v_add_co_u32_e32 v94, vcc, s25, v218
	s_nop 1
	v_addc_co_u32_e32 v95, vcc, 0, v219, vcc
	global_load_dwordx4 v[94:97], v[94:95], off nt
	v_add_co_u32_e32 v98, vcc, s29, v218
	s_nop 1
	v_addc_co_u32_e32 v99, vcc, 0, v219, vcc
	global_load_dwordx4 v[98:101], v[98:99], off nt
	v_add_co_u32_e32 v102, vcc, s30, v218
	s_nop 1
	v_addc_co_u32_e32 v103, vcc, 0, v219, vcc
	global_load_dwordx4 v[102:105], v[102:103], off nt
	s_add_u32 s58, s58, 0x1200000
	s_addc_u32 s59, s59, 0
	v_add_u32_e32 v37, 0x2000, v2
	v_add_u32_e32 v220, 0x4000, v2
	v_add_u32_e32 v221, 0x6000, v2
	ds_read2_b32 v[40:41], v2 offset1:32
	ds_read2_b32 v[44:45], v2 offset0:64 offset1:96
	ds_read2_b32 v[46:47], v2 offset0:128 offset1:160
	ds_read2_b32 v[106:107], v2 offset0:192 offset1:224
	ds_read2_b32 v[108:109], v37 offset1:32
	ds_read2_b32 v[110:111], v220 offset1:32
	ds_read2_b32 v[112:113], v221 offset1:32
	ds_read2_b32 v[114:115], v37 offset0:64 offset1:96
	ds_read2_b32 v[116:117], v220 offset0:64 offset1:96
	ds_read2_b32 v[118:119], v221 offset0:64 offset1:96
	ds_read2_b32 v[120:121], v37 offset0:128 offset1:160
	ds_read2_b32 v[122:123], v220 offset0:128 offset1:160
	ds_read2_b32 v[124:125], v221 offset0:128 offset1:160
	ds_read2_b32 v[126:127], v37 offset0:192 offset1:224
	ds_read2_b32 v[128:129], v220 offset0:192 offset1:224
	ds_read2_b32 v[130:131], v221 offset0:192 offset1:224
	s_waitcnt lgkmcnt(0)
	v_mov_b32_e32 v138, v109
	v_mov_b32_e32 v42, v41
	v_mov_b32_e32 v140, v111
	v_mov_b32_e32 v142, v113
	v_mov_b32_e32 v132, v45
	v_mov_b32_e32 v144, v115
	v_mov_b32_e32 v146, v117
	v_mov_b32_e32 v148, v119
	v_mov_b32_e32 v134, v47
	v_mov_b32_e32 v150, v121
	v_mov_b32_e32 v152, v123
	v_mov_b32_e32 v154, v125
	v_mov_b32_e32 v136, v107
	v_mov_b32_e32 v156, v127
	v_mov_b32_e32 v158, v129
	v_mov_b32_e32 v160, v131
	v_add_u32_e32 v2, 0x400, v2
	s_waitcnt vmcnt(15)
	v_pk_fma_f32 v[16:17], v[186:187], v[40:41], v[16:17] op_sel_hi:[1,0,1]
	v_pk_fma_f32 v[18:19], v[188:189], v[40:41], v[18:19] op_sel_hi:[1,0,1]
	v_pk_fma_f32 v[12:13], v[186:187], v[108:109], v[12:13] op_sel_hi:[1,0,1]
	v_pk_fma_f32 v[14:15], v[188:189], v[108:109], v[14:15] op_sel_hi:[1,0,1]
	v_pk_fma_f32 v[8:9], v[186:187], v[110:111], v[8:9] op_sel_hi:[1,0,1]
	v_pk_fma_f32 v[10:11], v[188:189], v[110:111], v[10:11] op_sel_hi:[1,0,1]
	v_pk_fma_f32 v[4:5], v[186:187], v[112:113], v[4:5] op_sel_hi:[1,0,1]
	v_pk_fma_f32 v[6:7], v[188:189], v[112:113], v[6:7] op_sel_hi:[1,0,1]
	s_waitcnt vmcnt(14)
	v_pk_fma_f32 v[16:17], v[190:191], v[42:43], v[16:17] op_sel_hi:[1,0,1]
	v_pk_fma_f32 v[18:19], v[192:193], v[42:43], v[18:19] op_sel_hi:[1,0,1]
	v_pk_fma_f32 v[12:13], v[190:191], v[138:139], v[12:13] op_sel_hi:[1,0,1]
	v_pk_fma_f32 v[14:15], v[192:193], v[138:139], v[14:15] op_sel_hi:[1,0,1]
	v_pk_fma_f32 v[8:9], v[190:191], v[140:141], v[8:9] op_sel_hi:[1,0,1]
	v_pk_fma_f32 v[10:11], v[192:193], v[140:141], v[10:11] op_sel_hi:[1,0,1]
	v_pk_fma_f32 v[4:5], v[190:191], v[142:143], v[4:5] op_sel_hi:[1,0,1]
	v_pk_fma_f32 v[6:7], v[192:193], v[142:143], v[6:7] op_sel_hi:[1,0,1]
	s_waitcnt vmcnt(13)
; __device__ __forceinline__ void phase_prep(const Params& P, LAS unsigned char* lds, int l, const XcdBarrier& bar) {
;     ...
; #pragma unroll 8
;         for (int kk = 0; kk < 64; ++kk) { const f32x4 wv = __builtin_nontemporal_load((const f32x4*)(wp + (size_t)kk * 32 * NMOD)); const int k = kg + 32 * kk;
;             a0 += wv * sc[k]; a1 += wv * sc[DM + k]; a2 += wv * sc[2 * DM + k]; a3 += wv * sc[3 * DM + k]; }
	v_pk_fma_f32 v[18:19], v[196:197], v[44:45], v[18:19] op_sel_hi:[1,0,1]
	v_pk_fma_f32 v[16:17], v[194:195], v[44:45], v[16:17] op_sel_hi:[1,0,1]
	v_pk_fma_f32 v[14:15], v[196:197], v[114:115], v[14:15] op_sel_hi:[1,0,1]
	v_pk_fma_f32 v[12:13], v[194:195], v[114:115], v[12:13] op_sel_hi:[1,0,1]
	v_pk_fma_f32 v[10:11], v[196:197], v[116:117], v[10:11] op_sel_hi:[1,0,1]
	v_pk_fma_f32 v[8:9], v[194:195], v[116:117], v[8:9] op_sel_hi:[1,0,1]
	v_pk_fma_f32 v[6:7], v[196:197], v[118:119], v[6:7] op_sel_hi:[1,0,1]
	v_pk_fma_f32 v[4:5], v[194:195], v[118:119], v[4:5] op_sel_hi:[1,0,1]
	s_waitcnt vmcnt(12)
	v_pk_fma_f32 v[18:19], v[200:201], v[132:133], v[18:19] op_sel_hi:[1,0,1]
	v_pk_fma_f32 v[16:17], v[198:199], v[132:133], v[16:17] op_sel_hi:[1,0,1]
	v_pk_fma_f32 v[14:15], v[200:201], v[144:145], v[14:15] op_sel_hi:[1,0,1]
	v_pk_fma_f32 v[12:13], v[198:199], v[144:145], v[12:13] op_sel_hi:[1,0,1]
	v_pk_fma_f32 v[10:11], v[200:201], v[146:147], v[10:11] op_sel_hi:[1,0,1]
	v_pk_fma_f32 v[8:9], v[198:199], v[146:147], v[8:9] op_sel_hi:[1,0,1]
	v_pk_fma_f32 v[6:7], v[200:201], v[148:149], v[6:7] op_sel_hi:[1,0,1]
	v_pk_fma_f32 v[4:5], v[198:199], v[148:149], v[4:5] op_sel_hi:[1,0,1]
	s_waitcnt vmcnt(11)
	v_pk_fma_f32 v[18:19], v[204:205], v[46:47], v[18:19] op_sel_hi:[1,0,1]
	v_pk_fma_f32 v[16:17], v[202:203], v[46:47], v[16:17] op_sel_hi:[1,0,1]
	v_pk_fma_f32 v[14:15], v[204:205], v[120:121], v[14:15] op_sel_hi:[1,0,1]
	v_pk_fma_f32 v[12:13], v[202:203], v[120:121], v[12:13] op_sel_hi:[1,0,1]
	v_pk_fma_f32 v[10:11], v[204:205], v[122:123], v[10:11] op_sel_hi:[1,0,1]
	v_pk_fma_f32 v[8:9], v[202:203], v[122:123], v[8:9] op_sel_hi:[1,0,1]
	v_pk_fma_f32 v[6:7], v[204:205], v[124:125], v[6:7] op_sel_hi:[1,0,1]
	v_pk_fma_f32 v[4:5], v[202:203], v[124:125], v[4:5] op_sel_hi:[1,0,1]
	s_waitcnt vmcnt(10)
	v_pk_fma_f32 v[18:19], v[208:209], v[134:135], v[18:19] op_sel_hi:[1,0,1]
	v_pk_fma_f32 v[16:17], v[206:207], v[134:135], v[16:17] op_sel_hi:[1,0,1]
	v_pk_fma_f32 v[14:15], v[208:209], v[150:151], v[14:15] op_sel_hi:[1,0,1]
	v_pk_fma_f32 v[12:13], v[206:207], v[150:151], v[12:13] op_sel_hi:[1,0,1]
	v_pk_fma_f32 v[10:11], v[208:209], v[152:153], v[10:11] op_sel_hi:[1,0,1]
	v_pk_fma_f32 v[8:9], v[206:207], v[152:153], v[8:9] op_sel_hi:[1,0,1]
	v_pk_fma_f32 v[6:7], v[208:209], v[154:155], v[6:7] op_sel_hi:[1,0,1]
	v_pk_fma_f32 v[4:5], v[206:207], v[154:155], v[4:5] op_sel_hi:[1,0,1]
	s_waitcnt vmcnt(9)
	v_pk_fma_f32 v[18:19], v[212:213], v[106:107], v[18:19] op_sel_hi:[1,0,1]
	v_pk_fma_f32 v[16:17], v[210:211], v[106:107], v[16:17] op_sel_hi:[1,0,1]
	v_pk_fma_f32 v[14:15], v[212:213], v[126:127], v[14:15] op_sel_hi:[1,0,1]
	v_pk_fma_f32 v[12:13], v[210:211], v[126:127], v[12:13] op_sel_hi:[1,0,1]
	v_pk_fma_f32 v[10:11], v[212:213], v[128:129], v[10:11] op_sel_hi:[1,0,1]
	v_pk_fma_f32 v[8:9], v[210:211], v[128:129], v[8:9] op_sel_hi:[1,0,1]
	v_pk_fma_f32 v[6:7], v[212:213], v[130:131], v[6:7] op_sel_hi:[1,0,1]
	v_pk_fma_f32 v[4:5], v[210:211], v[130:131], v[4:5] op_sel_hi:[1,0,1]
	s_waitcnt vmcnt(8)
	v_pk_fma_f32 v[18:19], v[216:217], v[136:137], v[18:19] op_sel_hi:[1,0,1]
	v_pk_fma_f32 v[16:17], v[214:215], v[136:137], v[16:17] op_sel_hi:[1,0,1]
	v_pk_fma_f32 v[14:15], v[216:217], v[156:157], v[14:15] op_sel_hi:[1,0,1]
	v_pk_fma_f32 v[12:13], v[214:215], v[156:157], v[12:13] op_sel_hi:[1,0,1]
	v_pk_fma_f32 v[10:11], v[216:217], v[158:159], v[10:11] op_sel_hi:[1,0,1]
	v_pk_fma_f32 v[8:9], v[214:215], v[158:159], v[8:9] op_sel_hi:[1,0,1]
	v_pk_fma_f32 v[6:7], v[216:217], v[160:161], v[6:7] op_sel_hi:[1,0,1]
	v_pk_fma_f32 v[4:5], v[214:215], v[160:161], v[4:5] op_sel_hi:[1,0,1]
	s_cmp_eq_u32 s58, 0x7e00000
	s_cbranch_scc0 .Lada_loop
	v_lshl_add_u64 v[218:219], v[38:39], 0, s[58:59]
	global_load_dwordx4 v[186:189], v[218:219], off nt
	v_add_co_u32_e32 v190, vcc, s2, v218
	s_nop 1
	v_addc_co_u32_e32 v191, vcc, 0, v219, vcc
	global_load_dwordx4 v[190:193], v[190:191], off nt
	v_add_co_u32_e32 v194, vcc, s9, v218
	s_nop 1
	v_addc_co_u32_e32 v195, vcc, 0, v219, vcc
	global_load_dwordx4 v[194:197], v[194:195], off nt
	v_add_co_u32_e32 v198, vcc, s19, v218
	s_nop 1
	v_addc_co_u32_e32 v199, vcc, 0, v219, vcc
	global_load_dwordx4 v[198:201], v[198:199], off nt
	v_add_co_u32_e32 v202, vcc, s24, v218
	s_nop 1
	v_addc_co_u32_e32 v203, vcc, 0, v219, vcc
	global_load_dwordx4 v[202:205], v[202:203], off nt
	v_add_co_u32_e32 v206, vcc, s25, v218
	s_nop 1
	v_addc_co_u32_e32 v207, vcc, 0, v219, vcc
	global_load_dwordx4 v[206:209], v[206:207], off nt
	v_add_co_u32_e32 v210, vcc, s29, v218
	s_nop 1
	v_addc_co_u32_e32 v211, vcc, 0, v219, vcc
	global_load_dwordx4 v[210:213], v[210:211], off nt
	v_add_co_u32_e32 v214, vcc, s30, v218
	s_nop 1
	v_addc_co_u32_e32 v215, vcc, 0, v219, vcc
	global_load_dwordx4 v[214:217], v[214:215], off nt
	s_add_u32 s58, s58, 0x1200000
	s_addc_u32 s59, s59, 0
	v_add_u32_e32 v37, 0x2000, v2
	v_add_u32_e32 v220, 0x4000, v2
	v_add_u32_e32 v221, 0x6000, v2
	ds_read2_b32 v[40:41], v2 offset1:32
	ds_read2_b32 v[44:45], v2 offset0:64 offset1:96
	ds_read2_b32 v[46:47], v2 offset0:128 offset1:160
	ds_read2_b32 v[106:107], v2 offset0:192 offset1:224
	ds_read2_b32 v[108:109], v37 offset1:32
	ds_read2_b32 v[110:111], v220 offset1:32
	ds_read2_b32 v[112:113], v221 offset1:32
	ds_read2_b32 v[114:115], v37 offset0:64 offset1:96
	ds_read2_b32 v[116:117], v220 offset0:64 offset1:96
	ds_read2_b32 v[118:119], v221 offset0:64 offset1:96
	ds_read2_b32 v[120:121], v37 offset0:128 offset1:160
	ds_read2_b32 v[122:123], v220 offset0:128 offset1:160
	ds_read2_b32 v[124:125], v221 offset0:128 offset1:160
	ds_read2_b32 v[126:127], v37 offset0:192 offset1:224
	ds_read2_b32 v[128:129], v220 offset0:192 offset1:224
	ds_read2_b32 v[130:131], v221 offset0:192 offset1:224
	s_waitcnt lgkmcnt(0)
; __device__ __forceinline__ void phase_prep(const Params& P, LAS unsigned char* lds, int l, const XcdBarrier& bar) {
;     ...
; #pragma unroll 8
;         for (int kk = 0; kk < 64; ++kk) { const f32x4 wv = __builtin_nontemporal_load((const f32x4*)(wp + (size_t)kk * 32 * NMOD)); const int k = kg + 32 * kk;
;             a0 += wv * sc[k]; a1 += wv * sc[DM + k]; a2 += wv * sc[2 * DM + k]; a3 += wv * sc[3 * DM + k]; }
	v_mov_b32_e32 v138, v109
	v_mov_b32_e32 v42, v41
	v_mov_b32_e32 v140, v111
	v_mov_b32_e32 v142, v113
	v_mov_b32_e32 v132, v45
	v_mov_b32_e32 v144, v115
	v_mov_b32_e32 v146, v117
	v_mov_b32_e32 v148, v119
	v_mov_b32_e32 v134, v47
	v_mov_b32_e32 v150, v121
	v_mov_b32_e32 v152, v123
	v_mov_b32_e32 v154, v125
	v_mov_b32_e32 v136, v107
	v_mov_b32_e32 v156, v127
	v_mov_b32_e32 v158, v129
	v_mov_b32_e32 v160, v131
	v_add_u32_e32 v2, 0x400, v2
	s_waitcnt vmcnt(15)
	v_pk_fma_f32 v[16:17], v[74:75], v[40:41], v[16:17] op_sel_hi:[1,0,1]
	v_pk_fma_f32 v[18:19], v[76:77], v[40:41], v[18:19] op_sel_hi:[1,0,1]
	v_pk_fma_f32 v[12:13], v[74:75], v[108:109], v[12:13] op_sel_hi:[1,0,1]
	v_pk_fma_f32 v[14:15], v[76:77], v[108:109], v[14:15] op_sel_hi:[1,0,1]
	v_pk_fma_f32 v[8:9], v[74:75], v[110:111], v[8:9] op_sel_hi:[1,0,1]
	v_pk_fma_f32 v[10:11], v[76:77], v[110:111], v[10:11] op_sel_hi:[1,0,1]
	v_pk_fma_f32 v[4:5], v[74:75], v[112:113], v[4:5] op_sel_hi:[1,0,1]
	v_pk_fma_f32 v[6:7], v[76:77], v[112:113], v[6:7] op_sel_hi:[1,0,1]
	s_waitcnt vmcnt(14)
	v_pk_fma_f32 v[16:17], v[78:79], v[42:43], v[16:17] op_sel_hi:[1,0,1]
	v_pk_fma_f32 v[18:19], v[80:81], v[42:43], v[18:19] op_sel_hi:[1,0,1]
	v_pk_fma_f32 v[12:13], v[78:79], v[138:139], v[12:13] op_sel_hi:[1,0,1]
	v_pk_fma_f32 v[14:15], v[80:81], v[138:139], v[14:15] op_sel_hi:[1,0,1]
	v_pk_fma_f32 v[8:9], v[78:79], v[140:141], v[8:9] op_sel_hi:[1,0,1]
	v_pk_fma_f32 v[10:11], v[80:81], v[140:141], v[10:11] op_sel_hi:[1,0,1]
	v_pk_fma_f32 v[4:5], v[78:79], v[142:143], v[4:5] op_sel_hi:[1,0,1]
	v_pk_fma_f32 v[6:7], v[80:81], v[142:143], v[6:7] op_sel_hi:[1,0,1]
	s_waitcnt vmcnt(13)
	v_pk_fma_f32 v[18:19], v[84:85], v[44:45], v[18:19] op_sel_hi:[1,0,1]
	v_pk_fma_f32 v[16:17], v[82:83], v[44:45], v[16:17] op_sel_hi:[1,0,1]
	v_pk_fma_f32 v[14:15], v[84:85], v[114:115], v[14:15] op_sel_hi:[1,0,1]
	v_pk_fma_f32 v[12:13], v[82:83], v[114:115], v[12:13] op_sel_hi:[1,0,1]
	v_pk_fma_f32 v[10:11], v[84:85], v[116:117], v[10:11] op_sel_hi:[1,0,1]
	v_pk_fma_f32 v[8:9], v[82:83], v[116:117], v[8:9] op_sel_hi:[1,0,1]
	v_pk_fma_f32 v[6:7], v[84:85], v[118:119], v[6:7] op_sel_hi:[1,0,1]
	v_pk_fma_f32 v[4:5], v[82:83], v[118:119], v[4:5] op_sel_hi:[1,0,1]
	s_waitcnt vmcnt(12)
	v_pk_fma_f32 v[18:19], v[88:89], v[132:133], v[18:19] op_sel_hi:[1,0,1]
	v_pk_fma_f32 v[16:17], v[86:87], v[132:133], v[16:17] op_sel_hi:[1,0,1]
	v_pk_fma_f32 v[14:15], v[88:89], v[144:145], v[14:15] op_sel_hi:[1,0,1]
	v_pk_fma_f32 v[12:13], v[86:87], v[144:145], v[12:13] op_sel_hi:[1,0,1]
	v_pk_fma_f32 v[10:11], v[88:89], v[146:147], v[10:11] op_sel_hi:[1,0,1]
	v_pk_fma_f32 v[8:9], v[86:87], v[146:147], v[8:9] op_sel_hi:[1,0,1]
	v_pk_fma_f32 v[6:7], v[88:89], v[148:149], v[6:7] op_sel_hi:[1,0,1]
	v_pk_fma_f32 v[4:5], v[86:87], v[148:149], v[4:5] op_sel_hi:[1,0,1]
	s_waitcnt vmcnt(11)
	v_pk_fma_f32 v[18:19], v[92:93], v[46:47], v[18:19] op_sel_hi:[1,0,1]
	v_pk_fma_f32 v[16:17], v[90:91], v[46:47], v[16:17] op_sel_hi:[1,0,1]
	v_pk_fma_f32 v[14:15], v[92:93], v[120:121], v[14:15] op_sel_hi:[1,0,1]
	v_pk_fma_f32 v[12:13], v[90:91], v[120:121], v[12:13] op_sel_hi:[1,0,1]
	v_pk_fma_f32 v[10:11], v[92:93], v[122:123], v[10:11] op_sel_hi:[1,0,1]
	v_pk_fma_f32 v[8:9], v[90:91], v[122:123], v[8:9] op_sel_hi:[1,0,1]
	v_pk_fma_f32 v[6:7], v[92:93], v[124:125], v[6:7] op_sel_hi:[1,0,1]
	v_pk_fma_f32 v[4:5], v[90:91], v[124:125], v[4:5] op_sel_hi:[1,0,1]
	s_waitcnt vmcnt(10)
	v_pk_fma_f32 v[18:19], v[96:97], v[134:135], v[18:19] op_sel_hi:[1,0,1]
	v_pk_fma_f32 v[16:17], v[94:95], v[134:135], v[16:17] op_sel_hi:[1,0,1]
	v_pk_fma_f32 v[14:15], v[96:97], v[150:151], v[14:15] op_sel_hi:[1,0,1]
	v_pk_fma_f32 v[12:13], v[94:95], v[150:151], v[12:13] op_sel_hi:[1,0,1]
	v_pk_fma_f32 v[10:11], v[96:97], v[152:153], v[10:11] op_sel_hi:[1,0,1]
	v_pk_fma_f32 v[8:9], v[94:95], v[152:153], v[8:9] op_sel_hi:[1,0,1]
	v_pk_fma_f32 v[6:7], v[96:97], v[154:155], v[6:7] op_sel_hi:[1,0,1]
	v_pk_fma_f32 v[4:5], v[94:95], v[154:155], v[4:5] op_sel_hi:[1,0,1]
	s_waitcnt vmcnt(9)
	v_pk_fma_f32 v[18:19], v[100:101], v[106:107], v[18:19] op_sel_hi:[1,0,1]
	v_pk_fma_f32 v[16:17], v[98:99], v[106:107], v[16:17] op_sel_hi:[1,0,1]
	v_pk_fma_f32 v[14:15], v[100:101], v[126:127], v[14:15] op_sel_hi:[1,0,1]
	v_pk_fma_f32 v[12:13], v[98:99], v[126:127], v[12:13] op_sel_hi:[1,0,1]
	v_pk_fma_f32 v[10:11], v[100:101], v[128:129], v[10:11] op_sel_hi:[1,0,1]
	v_pk_fma_f32 v[8:9], v[98:99], v[128:129], v[8:9] op_sel_hi:[1,0,1]
	v_pk_fma_f32 v[6:7], v[100:101], v[130:131], v[6:7] op_sel_hi:[1,0,1]
	v_pk_fma_f32 v[4:5], v[98:99], v[130:131], v[4:5] op_sel_hi:[1,0,1]
	s_waitcnt vmcnt(8)
	v_pk_fma_f32 v[18:19], v[104:105], v[136:137], v[18:19] op_sel_hi:[1,0,1]
	v_pk_fma_f32 v[16:17], v[102:103], v[136:137], v[16:17] op_sel_hi:[1,0,1]
	v_pk_fma_f32 v[14:15], v[104:105], v[156:157], v[14:15] op_sel_hi:[1,0,1]
	v_pk_fma_f32 v[12:13], v[102:103], v[156:157], v[12:13] op_sel_hi:[1,0,1]
	v_pk_fma_f32 v[10:11], v[104:105], v[158:159], v[10:11] op_sel_hi:[1,0,1]
	v_pk_fma_f32 v[8:9], v[102:103], v[158:159], v[8:9] op_sel_hi:[1,0,1]
	v_pk_fma_f32 v[6:7], v[104:105], v[160:161], v[6:7] op_sel_hi:[1,0,1]
	v_pk_fma_f32 v[4:5], v[102:103], v[160:161], v[4:5] op_sel_hi:[1,0,1]
	v_add_u32_e32 v37, 0x2000, v2
	v_add_u32_e32 v220, 0x4000, v2
	v_add_u32_e32 v221, 0x6000, v2
	ds_read2_b32 v[40:41], v2 offset1:32
	ds_read2_b32 v[44:45], v2 offset0:64 offset1:96
	ds_read2_b32 v[46:47], v2 offset0:128 offset1:160
	ds_read2_b32 v[106:107], v2 offset0:192 offset1:224
	ds_read2_b32 v[108:109], v37 offset1:32
	ds_read2_b32 v[110:111], v220 offset1:32
	ds_read2_b32 v[112:113], v221 offset1:32
	ds_read2_b32 v[114:115], v37 offset0:64 offset1:96
	ds_read2_b32 v[116:117], v220 offset0:64 offset1:96
	ds_read2_b32 v[118:119], v221 offset0:64 offset1:96
	ds_read2_b32 v[120:121], v37 offset0:128 offset1:160
	ds_read2_b32 v[122:123], v220 offset0:128 offset1:160
	ds_read2_b32 v[124:125], v221 offset0:128 offset1:160
	ds_read2_b32 v[126:127], v37 offset0:192 offset1:224
	ds_read2_b32 v[128:129], v220 offset0:192 offset1:224
	ds_read2_b32 v[130:131], v221 offset0:192 offset1:224
	s_waitcnt lgkmcnt(0)
; __device__ __forceinline__ void phase_prep(const Params& P, LAS unsigned char* lds, int l, const XcdBarrier& bar) {
;     ...
; #pragma unroll 8
;         for (int kk = 0; kk < 64; ++kk) { const f32x4 wv = __builtin_nontemporal_load((const f32x4*)(wp + (size_t)kk * 32 * NMOD)); const int k = kg + 32 * kk;
;             a0 += wv * sc[k]; a1 += wv * sc[DM + k]; a2 += wv * sc[2 * DM + k]; a3 += wv * sc[3 * DM + k]; }
; #pragma unroll
;         for (int e = 0; e < 4; ++e) { red[kg * 256 + 0 * 64 + 4 * cq + e] = a0[e]; red[kg * 256 + 1 * 64 + 4 * cq + e] = a1[e]; red[kg * 256 + 2 * 64 + 4 * cq + e] = a2[e]; red[kg * 256 + 3 * 64 + 4 * cq + e] = a3[e]; }
;         __syncthreads();
	v_mov_b32_e32 v138, v109
	v_mov_b32_e32 v42, v41
	v_mov_b32_e32 v140, v111
	v_mov_b32_e32 v142, v113
	v_mov_b32_e32 v132, v45
	v_mov_b32_e32 v144, v115
	v_mov_b32_e32 v146, v117
	v_mov_b32_e32 v148, v119
	v_mov_b32_e32 v134, v47
	v_mov_b32_e32 v150, v121
	v_mov_b32_e32 v152, v123
	v_mov_b32_e32 v154, v125
	v_mov_b32_e32 v136, v107
	v_mov_b32_e32 v156, v127
	v_mov_b32_e32 v158, v129
	v_mov_b32_e32 v160, v131
	v_add_u32_e32 v2, 0x400, v2
	s_waitcnt vmcnt(7)
	v_pk_fma_f32 v[16:17], v[186:187], v[40:41], v[16:17] op_sel_hi:[1,0,1]
	v_pk_fma_f32 v[18:19], v[188:189], v[40:41], v[18:19] op_sel_hi:[1,0,1]
	v_pk_fma_f32 v[12:13], v[186:187], v[108:109], v[12:13] op_sel_hi:[1,0,1]
	v_pk_fma_f32 v[14:15], v[188:189], v[108:109], v[14:15] op_sel_hi:[1,0,1]
	v_pk_fma_f32 v[8:9], v[186:187], v[110:111], v[8:9] op_sel_hi:[1,0,1]
	v_pk_fma_f32 v[10:11], v[188:189], v[110:111], v[10:11] op_sel_hi:[1,0,1]
	v_pk_fma_f32 v[4:5], v[186:187], v[112:113], v[4:5] op_sel_hi:[1,0,1]
	v_pk_fma_f32 v[6:7], v[188:189], v[112:113], v[6:7] op_sel_hi:[1,0,1]
	s_waitcnt vmcnt(6)
	v_pk_fma_f32 v[16:17], v[190:191], v[42:43], v[16:17] op_sel_hi:[1,0,1]
	v_pk_fma_f32 v[18:19], v[192:193], v[42:43], v[18:19] op_sel_hi:[1,0,1]
	v_pk_fma_f32 v[12:13], v[190:191], v[138:139], v[12:13] op_sel_hi:[1,0,1]
	v_pk_fma_f32 v[14:15], v[192:193], v[138:139], v[14:15] op_sel_hi:[1,0,1]
	v_pk_fma_f32 v[8:9], v[190:191], v[140:141], v[8:9] op_sel_hi:[1,0,1]
	v_pk_fma_f32 v[10:11], v[192:193], v[140:141], v[10:11] op_sel_hi:[1,0,1]
	v_pk_fma_f32 v[4:5], v[190:191], v[142:143], v[4:5] op_sel_hi:[1,0,1]
	v_pk_fma_f32 v[6:7], v[192:193], v[142:143], v[6:7] op_sel_hi:[1,0,1]
	s_waitcnt vmcnt(5)
	v_pk_fma_f32 v[18:19], v[196:197], v[44:45], v[18:19] op_sel_hi:[1,0,1]
	v_pk_fma_f32 v[16:17], v[194:195], v[44:45], v[16:17] op_sel_hi:[1,0,1]
	v_pk_fma_f32 v[14:15], v[196:197], v[114:115], v[14:15] op_sel_hi:[1,0,1]
	v_pk_fma_f32 v[12:13], v[194:195], v[114:115], v[12:13] op_sel_hi:[1,0,1]
	v_pk_fma_f32 v[10:11], v[196:197], v[116:117], v[10:11] op_sel_hi:[1,0,1]
	v_pk_fma_f32 v[8:9], v[194:195], v[116:117], v[8:9] op_sel_hi:[1,0,1]
	v_pk_fma_f32 v[6:7], v[196:197], v[118:119], v[6:7] op_sel_hi:[1,0,1]
	v_pk_fma_f32 v[4:5], v[194:195], v[118:119], v[4:5] op_sel_hi:[1,0,1]
	s_waitcnt vmcnt(4)
	v_pk_fma_f32 v[18:19], v[200:201], v[132:133], v[18:19] op_sel_hi:[1,0,1]
	v_pk_fma_f32 v[16:17], v[198:199], v[132:133], v[16:17] op_sel_hi:[1,0,1]
	v_pk_fma_f32 v[14:15], v[200:201], v[144:145], v[14:15] op_sel_hi:[1,0,1]
	v_pk_fma_f32 v[12:13], v[198:199], v[144:145], v[12:13] op_sel_hi:[1,0,1]
	v_pk_fma_f32 v[10:11], v[200:201], v[146:147], v[10:11] op_sel_hi:[1,0,1]
	v_pk_fma_f32 v[8:9], v[198:199], v[146:147], v[8:9] op_sel_hi:[1,0,1]
	v_pk_fma_f32 v[6:7], v[200:201], v[148:149], v[6:7] op_sel_hi:[1,0,1]
	v_pk_fma_f32 v[4:5], v[198:199], v[148:149], v[4:5] op_sel_hi:[1,0,1]
	s_waitcnt vmcnt(3)
	v_pk_fma_f32 v[18:19], v[204:205], v[46:47], v[18:19] op_sel_hi:[1,0,1]
	v_pk_fma_f32 v[16:17], v[202:203], v[46:47], v[16:17] op_sel_hi:[1,0,1]
	v_pk_fma_f32 v[14:15], v[204:205], v[120:121], v[14:15] op_sel_hi:[1,0,1]
	v_pk_fma_f32 v[12:13], v[202:203], v[120:121], v[12:13] op_sel_hi:[1,0,1]
	v_pk_fma_f32 v[10:11], v[204:205], v[122:123], v[10:11] op_sel_hi:[1,0,1]
	v_pk_fma_f32 v[8:9], v[202:203], v[122:123], v[8:9] op_sel_hi:[1,0,1]
	v_pk_fma_f32 v[6:7], v[204:205], v[124:125], v[6:7] op_sel_hi:[1,0,1]
	v_pk_fma_f32 v[4:5], v[202:203], v[124:125], v[4:5] op_sel_hi:[1,0,1]
	s_waitcnt vmcnt(2)
	v_pk_fma_f32 v[18:19], v[208:209], v[134:135], v[18:19] op_sel_hi:[1,0,1]
	v_pk_fma_f32 v[16:17], v[206:207], v[134:135], v[16:17] op_sel_hi:[1,0,1]
	v_pk_fma_f32 v[14:15], v[208:209], v[150:151], v[14:15] op_sel_hi:[1,0,1]
	v_pk_fma_f32 v[12:13], v[206:207], v[150:151], v[12:13] op_sel_hi:[1,0,1]
	v_pk_fma_f32 v[10:11], v[208:209], v[152:153], v[10:11] op_sel_hi:[1,0,1]
	v_pk_fma_f32 v[8:9], v[206:207], v[152:153], v[8:9] op_sel_hi:[1,0,1]
	v_pk_fma_f32 v[6:7], v[208:209], v[154:155], v[6:7] op_sel_hi:[1,0,1]
	v_pk_fma_f32 v[4:5], v[206:207], v[154:155], v[4:5] op_sel_hi:[1,0,1]
	s_waitcnt vmcnt(1)
	v_pk_fma_f32 v[18:19], v[212:213], v[106:107], v[18:19] op_sel_hi:[1,0,1]
	v_pk_fma_f32 v[16:17], v[210:211], v[106:107], v[16:17] op_sel_hi:[1,0,1]
	v_pk_fma_f32 v[14:15], v[212:213], v[126:127], v[14:15] op_sel_hi:[1,0,1]
	v_pk_fma_f32 v[12:13], v[210:211], v[126:127], v[12:13] op_sel_hi:[1,0,1]
	v_pk_fma_f32 v[10:11], v[212:213], v[128:129], v[10:11] op_sel_hi:[1,0,1]
	v_pk_fma_f32 v[8:9], v[210:211], v[128:129], v[8:9] op_sel_hi:[1,0,1]
	v_pk_fma_f32 v[6:7], v[212:213], v[130:131], v[6:7] op_sel_hi:[1,0,1]
	v_pk_fma_f32 v[4:5], v[210:211], v[130:131], v[4:5] op_sel_hi:[1,0,1]
	s_waitcnt vmcnt(0)
	v_pk_fma_f32 v[18:19], v[216:217], v[136:137], v[18:19] op_sel_hi:[1,0,1]
	v_pk_fma_f32 v[16:17], v[214:215], v[136:137], v[16:17] op_sel_hi:[1,0,1]
	v_pk_fma_f32 v[14:15], v[216:217], v[156:157], v[14:15] op_sel_hi:[1,0,1]
	v_pk_fma_f32 v[12:13], v[214:215], v[156:157], v[12:13] op_sel_hi:[1,0,1]
	v_pk_fma_f32 v[10:11], v[216:217], v[158:159], v[10:11] op_sel_hi:[1,0,1]
	v_pk_fma_f32 v[8:9], v[214:215], v[158:159], v[8:9] op_sel_hi:[1,0,1]
	v_pk_fma_f32 v[6:7], v[216:217], v[160:161], v[6:7] op_sel_hi:[1,0,1]
	v_pk_fma_f32 v[4:5], v[214:215], v[160:161], v[4:5] op_sel_hi:[1,0,1]
	v_readlane_b32 s18, v247, 23
	v_readlane_b32 s19, v247, 24
	ds_write_b128 v69, v[16:19] offset:32768
	ds_write_b128 v69, v[12:15] offset:33024
	ds_write_b128 v69, v[8:11] offset:33280
	ds_write_b128 v69, v[4:7] offset:33536
	s_waitcnt lgkmcnt(0)
	s_barrier
; __device__ __forceinline__ void phase_prep(const Params& P, LAS unsigned char* lds, int l, const XcdBarrier& bar) {
;     ...
;         __syncthreads();
;         if (tid < 256) { float s = 0.f;
; #pragma unroll
;             for (int q = 0; q < 32; ++q) s += red[q * 256 + tid];
;             const int b = tid >> 6, col = col0 + (tid & 63);
;             mod[(size_t)(ll * NBATCH + b) * NMOD + col] = s + P.ada_b[(size_t)ll * NMOD + col]; }
	s_and_saveexec_b64 s[58:59], s[18:19]
	s_cbranch_execz .LBB0_270
	v_readlane_b32 s60, v250, 39
	v_or_b32_e32 v4, s54, v48
	s_mul_i32 s19, s8, 0x12000
	v_readlane_b32 s66, v250, 45
	v_ashrrev_i32_e32 v5, 31, v4
	s_mul_hi_i32 s9, s8, 0x12000
	v_readlane_b32 s67, v250, 46
	s_add_u32 s24, s66, s19
	s_addc_u32 s25, s67, s9
	v_lshlrev_b64 v[4:5], 2, v[4:5]
	v_lshl_add_u64 v[6:7], s[24:25], 0, v[4:5]
	global_load_dword v2, v[6:7], off
	ds_read2st64_b32 v[6:7], v70 offset0:128 offset1:132
	ds_read2st64_b32 v[8:9], v70 offset0:136 offset1:140
	ds_read2st64_b32 v[10:11], v70 offset0:144 offset1:148
	ds_read2st64_b32 v[12:13], v70 offset0:152 offset1:156
	ds_read2st64_b32 v[14:15], v70 offset0:160 offset1:164
	ds_read2st64_b32 v[16:17], v70 offset0:168 offset1:172
	ds_read2st64_b32 v[18:19], v70 offset0:176 offset1:180
	ds_read2st64_b32 v[38:39], v70 offset0:184 offset1:188
	ds_read2st64_b32 v[40:41], v70 offset0:192 offset1:196
	ds_read2st64_b32 v[42:43], v70 offset0:200 offset1:204
	ds_read2st64_b32 v[44:45], v70 offset0:208 offset1:212
	ds_read2st64_b32 v[46:47], v70 offset0:216 offset1:220
	ds_read2st64_b32 v[74:75], v70 offset0:224 offset1:228
	ds_read2st64_b32 v[76:77], v70 offset0:232 offset1:236
	ds_read2st64_b32 v[78:79], v70 offset0:240 offset1:244
	ds_read2st64_b32 v[80:81], v70 offset0:248 offset1:252
	s_waitcnt lgkmcnt(14)
	v_add_f32_e32 v6, 0, v6
	v_add_f32_e32 v6, v6, v7
	v_add_f32_e32 v6, v6, v8
	v_add_f32_e32 v6, v6, v9
	s_waitcnt lgkmcnt(13)
	v_add_f32_e32 v6, v6, v10
	v_add_f32_e32 v6, v6, v11
	s_waitcnt lgkmcnt(12)
	v_add_f32_e32 v6, v6, v12
	v_add_f32_e32 v6, v6, v13
	s_waitcnt lgkmcnt(11)
	v_add_f32_e32 v6, v6, v14
	v_add_f32_e32 v6, v6, v15
	s_waitcnt lgkmcnt(10)
	v_add_f32_e32 v6, v6, v16
	v_add_f32_e32 v6, v6, v17
	s_waitcnt lgkmcnt(9)
	v_add_f32_e32 v6, v6, v18
	v_add_f32_e32 v6, v6, v19
	s_waitcnt lgkmcnt(8)
	v_add_f32_e32 v6, v6, v38
	v_add_f32_e32 v6, v6, v39
	s_waitcnt lgkmcnt(7)
	v_add_f32_e32 v6, v6, v40
	v_add_f32_e32 v6, v6, v41
	s_waitcnt lgkmcnt(6)
	v_add_f32_e32 v6, v6, v42
	v_add_f32_e32 v6, v6, v43
	s_waitcnt lgkmcnt(5)
	v_add_f32_e32 v6, v6, v44
	v_add_f32_e32 v6, v6, v45
	s_waitcnt lgkmcnt(4)
	v_add_f32_e32 v6, v6, v46
	v_add_f32_e32 v6, v6, v47
	s_waitcnt lgkmcnt(3)
	v_add_f32_e32 v6, v6, v74
	v_add_f32_e32 v6, v6, v75
	s_waitcnt lgkmcnt(2)
	v_add_f32_e32 v6, v6, v76
	v_add_f32_e32 v6, v6, v77
	s_waitcnt lgkmcnt(1)
	v_add_f32_e32 v6, v6, v78
	v_add_f32_e32 v6, v6, v79
	v_lshl_add_u32 v37, s8, 2, v27
	v_mov_b64_e32 v[82:83], s[4:5]
	s_waitcnt lgkmcnt(0)
	v_add_f32_e32 v6, v6, v80
	v_mad_i64_i32 v[82:83], s[8:9], v37, s6, v[82:83]
	v_add_f32_e32 v6, v6, v81
	v_lshl_add_u64 v[4:5], v[82:83], 0, v[4:5]
	v_readlane_b32 s61, v250, 40
	v_readlane_b32 s62, v250, 41
	v_readlane_b32 s63, v250, 42
	v_readlane_b32 s64, v250, 43
	v_readlane_b32 s65, v250, 44
	v_readlane_b32 s68, v250, 47
	v_readlane_b32 s69, v250, 48
	v_readlane_b32 s70, v250, 49
	v_readlane_b32 s71, v250, 50
	v_readlane_b32 s72, v250, 51
	v_readlane_b32 s73, v250, 52
	v_readlane_b32 s74, v250, 53
	v_readlane_b32 s75, v250, 54
	s_waitcnt vmcnt(0)
	v_add_f32_e32 v2, v6, v2
	global_store_dword v[4:5], v2, off
	s_branch .LBB0_270
